# store_T epilogues: 16 image reads issued together, stores behind counted lgkmcnt
# speedup vs baseline: 1.0054x; 1.0054x over previous
.LBB0_246:
	s_add_i32 s10, s7, 0xffffa000
	s_cmp_lg_u32 s7, 0
	s_cselect_b32 s12, s10, 0xc000
	v_add_u32_e32 v131, s7, v150
	s_waitcnt vmcnt(6)
	s_barrier
	v_add_u32_e32 v133, s7, v149
	ds_read_b128 v[154:157], v131 offset:0
	ds_read_b128 v[158:161], v131 offset:0x400
	ds_read_b128 v[162:165], v131 offset:0x800
	ds_read_b128 v[166:169], v131 offset:0xc00
	v_add_u32_e32 v131, s12, v147
	ds_read_b128 v[170:173], v133 offset:0
	ds_read_b128 v[174:177], v133 offset:0x400
	ds_read_b128 v[178:181], v133 offset:0x800
	ds_read_b128 v[200:203], v133 offset:0xc00
	s_add_u32 s10, s8, s50
	s_addc_u32 s11, s9, s51
	v_readfirstlane_b32 s13, v131
	s_add_u32 s64, s5, s100
	s_addc_u32 s65, s6, 0
	s_sub_i32 s68, s13, s12
	s_lshr_b32 s68, s68, 1
	s_add_i32 s68, s68, s12
	s_addk_i32 s68, 0x4000
	s_waitcnt lgkmcnt(0)
	s_nop 0
	v_mfma_f32_16x16x32_bf16 v[126:129], v[154:157], v[170:173], v[126:129]
	ds_read_b128 v[204:207], v133 offset:0x1000
	v_mfma_f32_16x16x32_bf16 v[122:125], v[154:157], v[174:177], v[122:125]
	ds_read_b128 v[208:211], v133 offset:0x1400
	v_mfma_f32_16x16x32_bf16 v[118:121], v[154:157], v[178:181], v[118:121]
	ds_read_b128 v[212:215], v133 offset:0x1800
	v_mfma_f32_16x16x32_bf16 v[114:117], v[154:157], v[200:203], v[114:117]
	ds_read_b128 v[216:219], v133 offset:0x1c00
	v_mfma_f32_16x16x32_bf16 v[110:113], v[158:161], v[170:173], v[110:113]
	s_mov_b32 m0, s13
	s_nop 0
	global_load_lds_dwordx4 v0, s[10:11]
	v_mfma_f32_16x16x32_bf16 v[102:105], v[158:161], v[174:177], v[102:105]
	v_mfma_f32_16x16x32_bf16 v[94:97], v[158:161], v[178:181], v[94:97]
	v_mfma_f32_16x16x32_bf16 v[86:89], v[158:161], v[200:203], v[86:89]
	s_add_u32 m0, s13, 0x400
	s_nop 0
	global_load_lds_dwordx4 v130, s[10:11]
	v_mfma_f32_16x16x32_bf16 v[78:81], v[162:165], v[170:173], v[78:81]
	v_mfma_f32_16x16x32_bf16 v[70:73], v[162:165], v[174:177], v[70:73]
	v_mfma_f32_16x16x32_bf16 v[62:65], v[162:165], v[178:181], v[62:65]
	s_add_u32 m0, s13, 0x800
	s_nop 0
	global_load_lds_dwordx4 v132, s[10:11]
	v_mfma_f32_16x16x32_bf16 v[54:57], v[162:165], v[200:203], v[54:57]
	v_mfma_f32_16x16x32_bf16 v[46:49], v[166:169], v[170:173], v[46:49]
	v_mfma_f32_16x16x32_bf16 v[38:41], v[166:169], v[174:177], v[38:41]
	s_add_u32 m0, s13, 0xc00
	s_nop 0
	global_load_lds_dwordx4 v136, s[10:11]
	v_mfma_f32_16x16x32_bf16 v[30:33], v[166:169], v[178:181], v[30:33]
	v_mfma_f32_16x16x32_bf16 v[22:25], v[166:169], v[200:203], v[22:25]
	s_waitcnt lgkmcnt(0)
	s_nop 0
	v_mfma_f32_16x16x32_bf16 v[106:109], v[154:157], v[204:207], v[106:109]
	v_mfma_f32_16x16x32_bf16 v[98:101], v[154:157], v[208:211], v[98:101]
	v_mfma_f32_16x16x32_bf16 v[90:93], v[154:157], v[212:215], v[90:93]
	s_mov_b32 m0, s68
	s_nop 0
	global_load_lds_dwordx4 v138, s[64:65]
	v_mfma_f32_16x16x32_bf16 v[82:85], v[154:157], v[216:219], v[82:85]
	v_mfma_f32_16x16x32_bf16 v[74:77], v[158:161], v[204:207], v[74:77]
	v_mfma_f32_16x16x32_bf16 v[66:69], v[158:161], v[208:211], v[66:69]
	v_mfma_f32_16x16x32_bf16 v[58:61], v[158:161], v[212:215], v[58:61]
	v_mfma_f32_16x16x32_bf16 v[50:53], v[158:161], v[216:219], v[50:53]
	v_mfma_f32_16x16x32_bf16 v[42:45], v[162:165], v[204:207], v[42:45]
	s_add_u32 m0, s68, 0x400
	s_nop 0
	global_load_lds_dwordx4 v140, s[64:65]
	v_mfma_f32_16x16x32_bf16 v[34:37], v[162:165], v[208:211], v[34:37]
	v_mfma_f32_16x16x32_bf16 v[26:29], v[162:165], v[212:215], v[26:29]
	v_mfma_f32_16x16x32_bf16 v[18:21], v[162:165], v[216:219], v[18:21]
	v_mfma_f32_16x16x32_bf16 v[14:17], v[166:169], v[204:207], v[14:17]
	v_mfma_f32_16x16x32_bf16 v[10:13], v[166:169], v[208:211], v[10:13]
	v_mfma_f32_16x16x32_bf16 v[6:9], v[166:169], v[212:215], v[6:9]
	v_mfma_f32_16x16x32_bf16 v[2:5], v[166:169], v[216:219], v[2:5]
	s_add_i32 s10, s7, 0x6000
	s_cmpk_lg_u32 s7, 0xc000
	s_cselect_b32 s7, s10, 0
	s_addk_i32 s100, 0x400
	s_add_u32 s50, s50, s60
	s_addc_u32 s51, s51, 0
	s_cmpk_lg_i32 s100, 0x7800
	s_cbranch_scc1 .LBB0_246
	s_waitcnt vmcnt(6)
	s_barrier
	v_add_u32_e32 v0, s7, v150
	v_add_u32_e32 v140, s7, v149
	ds_read_b128 v[130:133], v0 offset:0
	ds_read_b128 v[136:139], v0 offset:0x400
	ds_read_b128 v[154:157], v0 offset:0x800
	ds_read_b128 v[158:161], v0 offset:0xc00
	ds_read_b128 v[162:165], v140 offset:0
	ds_read_b128 v[166:169], v140 offset:0x400
	ds_read_b128 v[170:173], v140 offset:0x800
	ds_read_b128 v[174:177], v140 offset:0xc00
	ds_read_b128 v[178:181], v140 offset:0x1000
	ds_read_b128 v[200:203], v140 offset:0x1400
	ds_read_b128 v[204:207], v140 offset:0x1800
	ds_read_b128 v[208:211], v140 offset:0x1c00
	s_lshl_b32 s49, s4, 8
	s_waitcnt lgkmcnt(4)
	s_nop 0
	v_mfma_f32_16x16x32_bf16 v[126:129], v[130:133], v[162:165], v[126:129]
	v_mfma_f32_16x16x32_bf16 v[118:121], v[130:133], v[170:173], v[118:121]
	v_mfma_f32_16x16x32_bf16 v[114:117], v[130:133], v[174:177], v[114:117]
	v_mfma_f32_16x16x32_bf16 v[110:113], v[136:139], v[162:165], v[110:113]
	v_mfma_f32_16x16x32_bf16 v[102:105], v[136:139], v[166:169], v[102:105]
	v_mfma_f32_16x16x32_bf16 v[94:97], v[136:139], v[170:173], v[94:97]
	v_mfma_f32_16x16x32_bf16 v[86:89], v[136:139], v[174:177], v[86:89]
	v_mfma_f32_16x16x32_bf16 v[70:73], v[154:157], v[166:169], v[70:73]
	v_mfma_f32_16x16x32_bf16 v[62:65], v[154:157], v[170:173], v[62:65]
	v_mfma_f32_16x16x32_bf16 v[54:57], v[154:157], v[174:177], v[54:57]
	v_mfma_f32_16x16x32_bf16 v[46:49], v[158:161], v[162:165], v[46:49]
	v_mfma_f32_16x16x32_bf16 v[38:41], v[158:161], v[166:169], v[38:41]
	v_mfma_f32_16x16x32_bf16 v[30:33], v[158:161], v[170:173], v[30:33]
	v_mfma_f32_16x16x32_bf16 v[22:25], v[158:161], v[174:177], v[22:25]
	v_mfma_f32_16x16x32_bf16 v[212:215], v[130:133], v[166:169], v[122:125]
	v_mfma_f32_16x16x32_bf16 v[216:219], v[154:157], v[162:165], v[78:81]
	s_waitcnt lgkmcnt(0)
	s_nop 0
	v_mfma_f32_16x16x32_bf16 v[174:177], v[136:139], v[178:181], v[74:77]
	v_mfma_f32_16x16x32_bf16 v[220:223], v[136:139], v[200:203], v[66:69]
	v_mfma_f32_16x16x32_bf16 v[224:227], v[136:139], v[204:207], v[58:61]
	v_mfma_f32_16x16x32_bf16 v[50:53], v[136:139], v[208:211], v[50:53]
	v_mfma_f32_16x16x32_bf16 v[136:139], v[154:157], v[178:181], v[42:45]
	v_mfma_f32_16x16x32_bf16 v[34:37], v[154:157], v[200:203], v[34:37]
	v_mfma_f32_16x16x32_bf16 v[6:9], v[158:161], v[204:207], v[6:9]
	v_mfma_f32_16x16x32_bf16 v[162:165], v[130:133], v[178:181], v[106:109]
	v_mfma_f32_16x16x32_bf16 v[166:169], v[130:133], v[200:203], v[98:101]
	v_mfma_f32_16x16x32_bf16 v[170:173], v[130:133], v[204:207], v[90:93]
	v_mfma_f32_16x16x32_bf16 v[130:133], v[130:133], v[208:211], v[82:85]
	v_mfma_f32_16x16x32_bf16 v[228:231], v[154:157], v[204:207], v[26:29]
	v_mfma_f32_16x16x32_bf16 v[154:157], v[154:157], v[208:211], v[18:21]
	v_mfma_f32_16x16x32_bf16 v[178:181], v[158:161], v[178:181], v[14:17]
	v_mfma_f32_16x16x32_bf16 v[200:203], v[158:161], v[200:203], v[10:13]
	v_mfma_f32_16x16x32_bf16 v[158:161], v[158:161], v[208:211], v[2:5]
	s_waitcnt vmcnt(0)
	s_barrier
	ds_read_b128 v[2:5], v151 offset:0
	ds_read_b128 v[14:17], v151 offset:0x400
	ds_read_b128 v[204:207], v151 offset:0x800
	ds_read_b128 v[208:211], v151 offset:0xc00
	ds_read_b128 v[10:13], v152 offset:0
	ds_read_b128 v[18:21], v152 offset:0x400
	ds_read_b128 v[26:29], v152 offset:0x800
	ds_read_b128 v[42:45], v152 offset:0xc00
	ds_read_b128 v[232:235], v152 offset:0x1000
	ds_read_b128 v[236:239], v152 offset:0x1400
	ds_read_b128 v[240:243], v152 offset:0x1800
	ds_read_b128 v[244:247], v152 offset:0x1c00
	s_nop 0
	s_waitcnt lgkmcnt(4)
	s_nop 0
	v_mfma_f32_16x16x32_bf16 v[122:125], v[2:5], v[10:13], v[126:129]
	v_mfma_f32_16x16x32_bf16 v[106:109], v[2:5], v[18:21], v[212:215]
	v_mfma_f32_16x16x32_bf16 v[90:93], v[2:5], v[26:29], v[118:121]
	v_mfma_f32_16x16x32_bf16 v[74:77], v[2:5], v[42:45], v[114:117]
	v_mfma_f32_16x16x32_bf16 v[126:129], v[14:17], v[10:13], v[110:113]
	v_mfma_f32_16x16x32_bf16 v[110:113], v[14:17], v[18:21], v[102:105]
	v_mfma_f32_16x16x32_bf16 v[94:97], v[14:17], v[26:29], v[94:97]
	v_mfma_f32_16x16x32_bf16 v[78:81], v[14:17], v[42:45], v[86:89]
	v_mfma_f32_16x16x32_bf16 v[114:117], v[204:207], v[10:13], v[216:219]
	v_mfma_f32_16x16x32_bf16 v[98:101], v[204:207], v[18:21], v[70:73]
	v_mfma_f32_16x16x32_bf16 v[82:85], v[204:207], v[26:29], v[62:65]
	v_mfma_f32_16x16x32_bf16 v[66:69], v[204:207], v[42:45], v[54:57]
	v_mfma_f32_16x16x32_bf16 v[118:121], v[208:211], v[10:13], v[46:49]
	v_mfma_f32_16x16x32_bf16 v[102:105], v[208:211], v[18:21], v[38:41]
	v_mfma_f32_16x16x32_bf16 v[86:89], v[208:211], v[26:29], v[30:33]
	v_mfma_f32_16x16x32_bf16 v[70:73], v[208:211], v[42:45], v[22:25]
	s_waitcnt lgkmcnt(0)
	s_nop 0
	v_mfma_f32_16x16x32_bf16 v[58:61], v[2:5], v[232:235], v[162:165]
	v_mfma_f32_16x16x32_bf16 v[42:45], v[2:5], v[236:239], v[166:169]
	v_mfma_f32_16x16x32_bf16 v[26:29], v[2:5], v[240:243], v[170:173]
	v_mfma_f32_16x16x32_bf16 v[10:13], v[2:5], v[244:247], v[130:133]
	v_mfma_f32_16x16x32_bf16 v[62:65], v[14:17], v[232:235], v[174:177]
	v_mfma_f32_16x16x32_bf16 v[46:49], v[14:17], v[236:239], v[220:223]
	v_mfma_f32_16x16x32_bf16 v[30:33], v[14:17], v[240:243], v[224:227]
	v_mfma_f32_16x16x32_bf16 v[14:17], v[14:17], v[244:247], v[50:53]
	v_mfma_f32_16x16x32_bf16 v[50:53], v[204:207], v[232:235], v[136:139]
	v_mfma_f32_16x16x32_bf16 v[34:37], v[204:207], v[236:239], v[34:37]
	v_mfma_f32_16x16x32_bf16 v[18:21], v[204:207], v[240:243], v[228:231]
	v_mfma_f32_16x16x32_bf16 v[2:5], v[204:207], v[244:247], v[154:157]
	v_mfma_f32_16x16x32_bf16 v[54:57], v[208:211], v[232:235], v[178:181]
	v_mfma_f32_16x16x32_bf16 v[38:41], v[208:211], v[236:239], v[200:203]
	v_mfma_f32_16x16x32_bf16 v[22:25], v[208:211], v[240:243], v[6:9]
	v_mfma_f32_16x16x32_bf16 v[6:9], v[208:211], v[244:247], v[158:161]
	v_mov_b32_e32 v136, v134
	s_mov_b64 s[50:51], -1
	s_and_b64 vcc, exec, s[22:23]
	s_barrier
	s_cbranch_vccz .LBB0_264
	s_and_b64 vcc, exec, s[0:1]
	s_cbranch_vccz .LBB0_250
	v_lshrrev_b32_e32 v0, 6, v136
	v_mul_lo_u32 v137, v0, s14
	v_and_b32_e32 v130, 15, v136
	v_and_or_b32 v0, v136, 48, v137
	s_movk_i32 s4, 0x90
	v_mad_u32_u24 v0, v130, s4, v0
	v_cvt_pk_bf16_f32 v130, v122, v123
	v_cvt_pk_bf16_f32 v131, v124, v125
	v_cvt_pk_bf16_f32 v132, v126, v127
	v_cvt_pk_bf16_f32 v133, v128, v129
	s_waitcnt vmcnt(0)
	ds_write_b128 v0, v[130:133]
	v_cvt_pk_bf16_f32 v130, v114, v115
	v_cvt_pk_bf16_f32 v131, v116, v117
	v_cvt_pk_bf16_f32 v132, v118, v119
	v_cvt_pk_bf16_f32 v133, v120, v121
	ds_write_b128 v0, v[130:133] offset:64
	v_cvt_pk_bf16_f32 v130, v106, v107
	v_cvt_pk_bf16_f32 v131, v108, v109
	v_cvt_pk_bf16_f32 v132, v110, v111
	v_cvt_pk_bf16_f32 v133, v112, v113
	ds_write_b128 v0, v[130:133] offset:2304
	v_cvt_pk_bf16_f32 v130, v98, v99
	v_cvt_pk_bf16_f32 v131, v100, v101
	v_cvt_pk_bf16_f32 v132, v102, v103
	v_cvt_pk_bf16_f32 v133, v104, v105
	ds_write_b128 v0, v[130:133] offset:2368
	v_cvt_pk_bf16_f32 v130, v90, v91
	v_cvt_pk_bf16_f32 v131, v92, v93
	v_cvt_pk_bf16_f32 v132, v94, v95
	v_cvt_pk_bf16_f32 v133, v96, v97
	ds_write_b128 v0, v[130:133] offset:4608
	v_cvt_pk_bf16_f32 v130, v82, v83
	v_cvt_pk_bf16_f32 v131, v84, v85
	v_cvt_pk_bf16_f32 v132, v86, v87
	v_cvt_pk_bf16_f32 v133, v88, v89
	ds_write_b128 v0, v[130:133] offset:4672
	v_cvt_pk_bf16_f32 v130, v74, v75
	v_cvt_pk_bf16_f32 v131, v76, v77
	v_cvt_pk_bf16_f32 v132, v78, v79
	v_cvt_pk_bf16_f32 v133, v80, v81
	ds_write_b128 v0, v[130:133] offset:6912
	v_cvt_pk_bf16_f32 v130, v66, v67
	v_cvt_pk_bf16_f32 v131, v68, v69
	v_cvt_pk_bf16_f32 v132, v70, v71
	v_cvt_pk_bf16_f32 v133, v72, v73
	ds_write_b128 v0, v[130:133] offset:6976
	v_cvt_pk_bf16_f32 v130, v58, v59
	v_cvt_pk_bf16_f32 v131, v60, v61
	v_cvt_pk_bf16_f32 v132, v62, v63
	v_cvt_pk_bf16_f32 v133, v64, v65
	ds_write_b128 v0, v[130:133] offset:9216
	v_cvt_pk_bf16_f32 v130, v50, v51
	v_cvt_pk_bf16_f32 v131, v52, v53
	v_cvt_pk_bf16_f32 v132, v54, v55
	v_cvt_pk_bf16_f32 v133, v56, v57
	ds_write_b128 v0, v[130:133] offset:9280
	v_cvt_pk_bf16_f32 v130, v42, v43
	v_cvt_pk_bf16_f32 v131, v44, v45
	v_cvt_pk_bf16_f32 v132, v46, v47
	v_cvt_pk_bf16_f32 v133, v48, v49
	ds_write_b128 v0, v[130:133] offset:11520
	v_cvt_pk_bf16_f32 v130, v34, v35
	v_cvt_pk_bf16_f32 v131, v36, v37
	v_cvt_pk_bf16_f32 v132, v38, v39
	v_cvt_pk_bf16_f32 v133, v40, v41
	ds_write_b128 v0, v[130:133] offset:11584
	v_cvt_pk_bf16_f32 v130, v26, v27
	v_cvt_pk_bf16_f32 v131, v28, v29
	v_cvt_pk_bf16_f32 v132, v30, v31
	v_cvt_pk_bf16_f32 v133, v32, v33
	ds_write_b128 v0, v[130:133] offset:13824
	v_cvt_pk_bf16_f32 v130, v18, v19
	v_cvt_pk_bf16_f32 v131, v20, v21
	v_cvt_pk_bf16_f32 v132, v22, v23
	v_cvt_pk_bf16_f32 v133, v24, v25
	ds_write_b128 v0, v[130:133] offset:13888
	v_cvt_pk_bf16_f32 v130, v10, v11
	v_cvt_pk_bf16_f32 v131, v12, v13
	v_cvt_pk_bf16_f32 v132, v14, v15
	v_cvt_pk_bf16_f32 v133, v16, v17
	ds_write_b128 v0, v[130:133] offset:16128
	v_cvt_pk_bf16_f32 v130, v2, v3
	v_cvt_pk_bf16_f32 v131, v4, v5
	v_cvt_pk_bf16_f32 v132, v6, v7
	v_cvt_pk_bf16_f32 v133, v8, v9
	ds_write_b128 v0, v[130:133] offset:16192
	v_and_b32_e32 v0, 0xffffff80, v136
	v_add_u32_e32 v130, s48, v0
	v_ashrrev_i32_e32 v131, 31, v130
	v_lshlrev_b64 v[130:131], 11, v[130:131]
	v_lshl_add_u64 v[130:131], s[38:39], 0, v[130:131]
	v_and_b32_e32 v0, 64, v136
	v_lshl_add_u64 v[130:131], s[46:47], 1, v[130:131]
	v_lshlrev_b32_e32 v0, 1, v0
	v_lshl_add_u64 v[138:139], v[130:131], 0, v[0:1]
	v_lshlrev_b32_e32 v0, 4, v136
	v_and_b32_e32 v0, 0x70, v0
	v_bfe_u32 v140, v136, 3, 3
	v_or_b32_e32 v130, v137, v0
	s_waitcnt lgkmcnt(0)
	v_mad_u32_u24 v137, v140, s4, v130
	ds_read_b128 v[66:69], v137
	ds_read_b128 v[70:73], v137 offset:1152
	ds_read_b128 v[74:77], v137 offset:2304
	ds_read_b128 v[78:81], v137 offset:3456
	ds_read_b128 v[82:85], v137 offset:4608
	ds_read_b128 v[86:89], v137 offset:5760
	ds_read_b128 v[90:93], v137 offset:6912
	ds_read_b128 v[94:97], v137 offset:8064
	ds_read_b128 v[98:101], v137 offset:9216
	ds_read_b128 v[102:105], v137 offset:10368
	ds_read_b128 v[106:109], v137 offset:11520
	ds_read_b128 v[110:113], v137 offset:12672
	ds_read_b128 v[114:117], v137 offset:13824
	ds_read_b128 v[118:121], v137 offset:14976
	ds_read_b128 v[122:125], v137 offset:16128
	ds_read_b128 v[126:129], v137 offset:17280
	v_lshl_add_u64 v[138:139], v[138:139], 0, v[0:1]
	v_lshlrev_b32_e32 v0, 11, v140
	v_lshl_add_u64 v[140:141], v[138:139], 0, v[0:1]
	s_mov_b64 s[50:51], 0
	s_waitcnt lgkmcnt(15)
	global_store_dwordx4 v[140:141], v[66:69], off
	v_or_b32_e32 v140, 0x4000, v0
	v_mov_b32_e32 v141, v1
	v_lshl_add_u64 v[140:141], v[138:139], 0, v[140:141]
	s_waitcnt lgkmcnt(14)
	global_store_dwordx4 v[140:141], v[70:73], off
	v_or_b32_e32 v140, 0x8000, v0
	v_mov_b32_e32 v141, v1
	v_lshl_add_u64 v[140:141], v[138:139], 0, v[140:141]
	s_waitcnt lgkmcnt(13)
	global_store_dwordx4 v[140:141], v[74:77], off
	v_or_b32_e32 v140, 0xc000, v0
	v_mov_b32_e32 v141, v1
	v_lshl_add_u64 v[140:141], v[138:139], 0, v[140:141]
	s_waitcnt lgkmcnt(12)
	global_store_dwordx4 v[140:141], v[78:81], off
	v_or_b32_e32 v140, 0x10000, v0
	v_mov_b32_e32 v141, v1
	v_lshl_add_u64 v[140:141], v[138:139], 0, v[140:141]
	s_waitcnt lgkmcnt(11)
	global_store_dwordx4 v[140:141], v[82:85], off
	v_or_b32_e32 v140, 0x14000, v0
	v_mov_b32_e32 v141, v1
	v_lshl_add_u64 v[140:141], v[138:139], 0, v[140:141]
	s_waitcnt lgkmcnt(10)
	global_store_dwordx4 v[140:141], v[86:89], off
	v_or_b32_e32 v140, 0x18000, v0
	v_mov_b32_e32 v141, v1
	v_lshl_add_u64 v[140:141], v[138:139], 0, v[140:141]
	s_waitcnt lgkmcnt(9)
	global_store_dwordx4 v[140:141], v[90:93], off
	v_or_b32_e32 v140, 0x1c000, v0
	v_mov_b32_e32 v141, v1
	v_lshl_add_u64 v[140:141], v[138:139], 0, v[140:141]
	s_waitcnt lgkmcnt(8)
	global_store_dwordx4 v[140:141], v[94:97], off
	v_or_b32_e32 v140, 0x20000, v0
	v_mov_b32_e32 v141, v1
	v_lshl_add_u64 v[140:141], v[138:139], 0, v[140:141]
	s_waitcnt lgkmcnt(7)
	global_store_dwordx4 v[140:141], v[98:101], off
	v_or_b32_e32 v140, 0x24000, v0
	v_mov_b32_e32 v141, v1
	v_lshl_add_u64 v[140:141], v[138:139], 0, v[140:141]
	s_waitcnt lgkmcnt(6)
	global_store_dwordx4 v[140:141], v[102:105], off
	v_or_b32_e32 v140, 0x28000, v0
	v_mov_b32_e32 v141, v1
	v_lshl_add_u64 v[140:141], v[138:139], 0, v[140:141]
	s_waitcnt lgkmcnt(5)
	global_store_dwordx4 v[140:141], v[106:109], off
	v_or_b32_e32 v140, 0x2c000, v0
	v_mov_b32_e32 v141, v1
	v_lshl_add_u64 v[140:141], v[138:139], 0, v[140:141]
	s_waitcnt lgkmcnt(4)
	global_store_dwordx4 v[140:141], v[110:113], off
	v_or_b32_e32 v140, 0x30000, v0
	v_mov_b32_e32 v141, v1
	v_lshl_add_u64 v[140:141], v[138:139], 0, v[140:141]
	s_waitcnt lgkmcnt(3)
	global_store_dwordx4 v[140:141], v[114:117], off
	v_or_b32_e32 v140, 0x34000, v0
	v_mov_b32_e32 v141, v1
	v_lshl_add_u64 v[140:141], v[138:139], 0, v[140:141]
	s_waitcnt lgkmcnt(2)
	global_store_dwordx4 v[140:141], v[118:121], off
	v_or_b32_e32 v140, 0x38000, v0
	v_mov_b32_e32 v141, v1
	v_lshl_add_u64 v[140:141], v[138:139], 0, v[140:141]
	v_or_b32_e32 v0, 0x3c000, v0
	s_waitcnt lgkmcnt(1)
	global_store_dwordx4 v[140:141], v[122:125], off
	v_lshl_add_u64 v[138:139], v[138:139], 0, v[0:1]
	s_waitcnt lgkmcnt(0)
	global_store_dwordx4 v[138:139], v[126:129], off
	s_waitcnt lgkmcnt(0)
	s_barrier
.LBB0_250:
	s_andn2_b64 vcc, exec, s[50:51]
	s_cbranch_vccnz .LBB0_263
	s_cmp_gt_i32 s80, 7
	s_mov_b64 s[50:51], -1
	s_cbranch_scc0 .LBB0_261
	s_cmp_gt_u32 s80, 15
	s_cbranch_scc0 .LBB0_258
	s_cmp_gt_u32 s80, 23
	v_cvt_pk_bf16_f32 v131, v124, v125
	s_cbranch_scc0 .LBB0_255
	v_lshrrev_b32_e32 v0, 6, v136
	v_mul_lo_u32 v137, v0, s14
	v_and_b32_e32 v130, 15, v136
	v_and_or_b32 v0, v136, 48, v137
	s_movk_i32 s4, 0x90
	v_mad_u32_u24 v0, v130, s4, v0
	v_cvt_pk_bf16_f32 v138, v114, v115
	v_cvt_pk_bf16_f32 v139, v116, v117
	v_cvt_pk_bf16_f32 v140, v118, v119
	v_cvt_pk_bf16_f32 v141, v120, v121
	s_waitcnt vmcnt(0)
	ds_write_b128 v0, v[138:141] offset:64
	v_cvt_pk_bf16_f32 v138, v106, v107
	v_cvt_pk_bf16_f32 v139, v108, v109
	v_cvt_pk_bf16_f32 v140, v110, v111
	v_cvt_pk_bf16_f32 v141, v112, v113
	ds_write_b128 v0, v[138:141] offset:2304
	v_cvt_pk_bf16_f32 v138, v98, v99
	v_cvt_pk_bf16_f32 v139, v100, v101
	v_cvt_pk_bf16_f32 v140, v102, v103
	v_cvt_pk_bf16_f32 v141, v104, v105
	ds_write_b128 v0, v[138:141] offset:2368
	v_cvt_pk_bf16_f32 v138, v90, v91
	v_cvt_pk_bf16_f32 v139, v92, v93
	v_cvt_pk_bf16_f32 v140, v94, v95
	v_cvt_pk_bf16_f32 v141, v96, v97
	ds_write_b128 v0, v[138:141] offset:4608
	v_cvt_pk_bf16_f32 v138, v82, v83
	v_cvt_pk_bf16_f32 v139, v84, v85
	v_cvt_pk_bf16_f32 v140, v86, v87
	v_cvt_pk_bf16_f32 v141, v88, v89
	ds_write_b128 v0, v[138:141] offset:4672
	v_cvt_pk_bf16_f32 v138, v74, v75
	v_cvt_pk_bf16_f32 v139, v76, v77
	v_cvt_pk_bf16_f32 v140, v78, v79
	v_cvt_pk_bf16_f32 v141, v80, v81
	ds_write_b128 v0, v[138:141] offset:6912
	v_cvt_pk_bf16_f32 v138, v66, v67
	v_cvt_pk_bf16_f32 v139, v68, v69
	v_cvt_pk_bf16_f32 v140, v70, v71
	v_cvt_pk_bf16_f32 v141, v72, v73
	ds_write_b128 v0, v[138:141] offset:6976
	v_cvt_pk_bf16_f32 v138, v58, v59
	v_cvt_pk_bf16_f32 v139, v60, v61
	v_cvt_pk_bf16_f32 v140, v62, v63
	v_cvt_pk_bf16_f32 v141, v64, v65
	ds_write_b128 v0, v[138:141] offset:9216
	v_cvt_pk_bf16_f32 v138, v50, v51
	v_cvt_pk_bf16_f32 v139, v52, v53
	v_cvt_pk_bf16_f32 v140, v54, v55
	v_cvt_pk_bf16_f32 v141, v56, v57
	ds_write_b128 v0, v[138:141] offset:9280
	v_cvt_pk_bf16_f32 v138, v42, v43
	v_cvt_pk_bf16_f32 v139, v44, v45
	v_cvt_pk_bf16_f32 v140, v46, v47
	v_cvt_pk_bf16_f32 v141, v48, v49
	ds_write_b128 v0, v[138:141] offset:11520
	v_cvt_pk_bf16_f32 v138, v34, v35
	v_cvt_pk_bf16_f32 v139, v36, v37
	v_cvt_pk_bf16_f32 v140, v38, v39
	v_cvt_pk_bf16_f32 v141, v40, v41
	ds_write_b128 v0, v[138:141] offset:11584
	v_cvt_pk_bf16_f32 v138, v26, v27
	v_cvt_pk_bf16_f32 v139, v28, v29
	v_cvt_pk_bf16_f32 v140, v30, v31
	v_cvt_pk_bf16_f32 v141, v32, v33
	ds_write_b128 v0, v[138:141] offset:13824
	v_cvt_pk_bf16_f32 v138, v18, v19
	v_cvt_pk_bf16_f32 v139, v20, v21
	v_cvt_pk_bf16_f32 v140, v22, v23
	v_cvt_pk_bf16_f32 v141, v24, v25
	ds_write_b128 v0, v[138:141] offset:13888
	v_cvt_pk_bf16_f32 v138, v10, v11
	v_cvt_pk_bf16_f32 v139, v12, v13
	v_cvt_pk_bf16_f32 v140, v14, v15
	v_cvt_pk_bf16_f32 v141, v16, v17
	v_cvt_pk_bf16_f32 v130, v122, v123
	v_cvt_pk_bf16_f32 v132, v126, v127
	v_cvt_pk_bf16_f32 v133, v128, v129
	ds_write_b128 v0, v[138:141] offset:16128
	v_cvt_pk_bf16_f32 v138, v2, v3
	v_cvt_pk_bf16_f32 v139, v4, v5
	v_cvt_pk_bf16_f32 v140, v6, v7
	v_cvt_pk_bf16_f32 v141, v8, v9
	ds_write_b128 v0, v[130:133]
	ds_write_b128 v0, v[138:141] offset:16192
	v_and_b32_e32 v0, 0xffffff80, v136
	v_add_u32_e32 v132, s48, v0
	v_ashrrev_i32_e32 v133, 31, v132
	v_lshlrev_b64 v[132:133], 11, v[132:133]
	v_lshl_add_u64 v[132:133], s[94:95], 0, v[132:133]
	s_mov_b32 s92, s46
	v_and_b32_e32 v0, 64, v136
	v_lshl_add_u64 v[132:133], s[92:93], 1, v[132:133]
	v_lshlrev_b32_e32 v0, 1, v0
	v_lshl_add_u64 v[132:133], v[132:133], 0, v[0:1]
	v_lshlrev_b32_e32 v0, 4, v136
	v_and_b32_e32 v0, 0x70, v0
	v_bfe_u32 v130, v136, 3, 3
	v_or_b32_e32 v137, v137, v0
	s_waitcnt lgkmcnt(0)
	v_mad_u32_u24 v137, v130, s4, v137
	ds_read_b128 v[66:69], v137
	ds_read_b128 v[70:73], v137 offset:1152
	ds_read_b128 v[74:77], v137 offset:2304
	ds_read_b128 v[78:81], v137 offset:3456
	ds_read_b128 v[82:85], v137 offset:4608
	ds_read_b128 v[86:89], v137 offset:5760
	ds_read_b128 v[90:93], v137 offset:6912
	ds_read_b128 v[94:97], v137 offset:8064
	ds_read_b128 v[98:101], v137 offset:9216
	ds_read_b128 v[102:105], v137 offset:10368
	ds_read_b128 v[106:109], v137 offset:11520
	ds_read_b128 v[110:113], v137 offset:12672
	ds_read_b128 v[114:117], v137 offset:13824
	ds_read_b128 v[118:121], v137 offset:14976
	ds_read_b128 v[122:125], v137 offset:16128
	ds_read_b128 v[126:129], v137 offset:17280
	v_lshl_add_u64 v[132:133], v[132:133], 0, v[0:1]
	s_mov_b64 s[4:5], 0x8ffe800
	v_lshl_add_u64 v[132:133], v[132:133], 0, s[4:5]
	v_lshlrev_b32_e32 v0, 11, v130
	v_lshl_add_u64 v[154:155], v[132:133], 0, v[0:1]
	s_waitcnt lgkmcnt(15)
	global_store_dwordx4 v[154:155], v[66:69], off
	v_or_b32_e32 v154, 0x4000, v0
	v_mov_b32_e32 v155, v1
	v_lshl_add_u64 v[154:155], v[132:133], 0, v[154:155]
	s_movk_i32 s82, 0x1bff
	s_waitcnt lgkmcnt(14)
	global_store_dwordx4 v[154:155], v[70:73], off
	v_or_b32_e32 v154, 0x8000, v0
	v_mov_b32_e32 v155, v1
	v_lshl_add_u64 v[154:155], v[132:133], 0, v[154:155]
	s_mov_b64 s[50:51], 0
	s_waitcnt lgkmcnt(13)
	global_store_dwordx4 v[154:155], v[74:77], off
	v_or_b32_e32 v154, 0xc000, v0
	v_mov_b32_e32 v155, v1
	v_lshl_add_u64 v[154:155], v[132:133], 0, v[154:155]
	s_waitcnt lgkmcnt(12)
	global_store_dwordx4 v[154:155], v[78:81], off
	v_or_b32_e32 v154, 0x10000, v0
	v_mov_b32_e32 v155, v1
	v_lshl_add_u64 v[154:155], v[132:133], 0, v[154:155]
	s_waitcnt lgkmcnt(11)
	global_store_dwordx4 v[154:155], v[82:85], off
	v_or_b32_e32 v154, 0x14000, v0
	v_mov_b32_e32 v155, v1
	v_lshl_add_u64 v[154:155], v[132:133], 0, v[154:155]
	s_waitcnt lgkmcnt(10)
	global_store_dwordx4 v[154:155], v[86:89], off
	v_or_b32_e32 v154, 0x18000, v0
	v_mov_b32_e32 v155, v1
	v_lshl_add_u64 v[154:155], v[132:133], 0, v[154:155]
	s_waitcnt lgkmcnt(9)
	global_store_dwordx4 v[154:155], v[90:93], off
	v_or_b32_e32 v154, 0x1c000, v0
	v_mov_b32_e32 v155, v1
	v_lshl_add_u64 v[154:155], v[132:133], 0, v[154:155]
	s_waitcnt lgkmcnt(8)
	global_store_dwordx4 v[154:155], v[94:97], off
	v_or_b32_e32 v154, 0x20000, v0
	v_mov_b32_e32 v155, v1
	v_lshl_add_u64 v[154:155], v[132:133], 0, v[154:155]
	s_waitcnt lgkmcnt(7)
	global_store_dwordx4 v[154:155], v[98:101], off
	v_or_b32_e32 v154, 0x24000, v0
	v_mov_b32_e32 v155, v1
	v_lshl_add_u64 v[154:155], v[132:133], 0, v[154:155]
	s_waitcnt lgkmcnt(6)
	global_store_dwordx4 v[154:155], v[102:105], off
	v_or_b32_e32 v154, 0x28000, v0
	v_mov_b32_e32 v155, v1
	v_lshl_add_u64 v[154:155], v[132:133], 0, v[154:155]
	s_waitcnt lgkmcnt(5)
	global_store_dwordx4 v[154:155], v[106:109], off
	v_or_b32_e32 v154, 0x2c000, v0
	v_mov_b32_e32 v155, v1
	v_lshl_add_u64 v[154:155], v[132:133], 0, v[154:155]
	s_waitcnt lgkmcnt(4)
	global_store_dwordx4 v[154:155], v[110:113], off
	v_or_b32_e32 v154, 0x30000, v0
	v_mov_b32_e32 v155, v1
	v_lshl_add_u64 v[154:155], v[132:133], 0, v[154:155]
	s_waitcnt lgkmcnt(3)
	global_store_dwordx4 v[154:155], v[114:117], off
	v_or_b32_e32 v154, 0x34000, v0
	v_mov_b32_e32 v155, v1
	v_lshl_add_u64 v[154:155], v[132:133], 0, v[154:155]
	s_waitcnt lgkmcnt(2)
	global_store_dwordx4 v[154:155], v[118:121], off
	v_or_b32_e32 v154, 0x38000, v0
	v_mov_b32_e32 v155, v1
	v_lshl_add_u64 v[154:155], v[132:133], 0, v[154:155]
	v_or_b32_e32 v0, 0x3c000, v0
	s_waitcnt lgkmcnt(1)
	global_store_dwordx4 v[154:155], v[122:125], off
	v_lshl_add_u64 v[132:133], v[132:133], 0, v[0:1]
	s_waitcnt lgkmcnt(0)
	global_store_dwordx4 v[132:133], v[126:129], off
	s_waitcnt lgkmcnt(0)
	s_barrier

.LBB0_258:
	s_andn2_b64 vcc, exec, s[50:51]
	s_cbranch_vccnz .LBB0_260
	v_lshrrev_b32_e32 v0, 6, v136
	v_mul_lo_u32 v137, v0, s14
	v_and_b32_e32 v130, 15, v136
	v_and_or_b32 v0, v136, 48, v137
	s_movk_i32 s4, 0x90
	v_mad_u32_u24 v0, v130, s4, v0
	v_cvt_pk_bf16_f32 v130, v122, v123
	v_cvt_pk_bf16_f32 v131, v124, v125
	v_cvt_pk_bf16_f32 v132, v126, v127
	v_cvt_pk_bf16_f32 v133, v128, v129
	s_waitcnt vmcnt(0)
	ds_write_b128 v0, v[130:133]
	v_cvt_pk_bf16_f32 v130, v114, v115
	v_cvt_pk_bf16_f32 v131, v116, v117
	v_cvt_pk_bf16_f32 v132, v118, v119
	v_cvt_pk_bf16_f32 v133, v120, v121
	ds_write_b128 v0, v[130:133] offset:64
	v_cvt_pk_bf16_f32 v130, v106, v107
	v_cvt_pk_bf16_f32 v131, v108, v109
	v_cvt_pk_bf16_f32 v132, v110, v111
	v_cvt_pk_bf16_f32 v133, v112, v113
	ds_write_b128 v0, v[130:133] offset:2304
	v_cvt_pk_bf16_f32 v130, v98, v99
	v_cvt_pk_bf16_f32 v131, v100, v101
	v_cvt_pk_bf16_f32 v132, v102, v103
	v_cvt_pk_bf16_f32 v133, v104, v105
	ds_write_b128 v0, v[130:133] offset:2368
	v_cvt_pk_bf16_f32 v130, v90, v91
	v_cvt_pk_bf16_f32 v131, v92, v93
	v_cvt_pk_bf16_f32 v132, v94, v95
	v_cvt_pk_bf16_f32 v133, v96, v97
	ds_write_b128 v0, v[130:133] offset:4608
	v_cvt_pk_bf16_f32 v130, v82, v83
	v_cvt_pk_bf16_f32 v131, v84, v85
	v_cvt_pk_bf16_f32 v132, v86, v87
	v_cvt_pk_bf16_f32 v133, v88, v89
	ds_write_b128 v0, v[130:133] offset:4672
	v_cvt_pk_bf16_f32 v130, v74, v75
	v_cvt_pk_bf16_f32 v131, v76, v77
	v_cvt_pk_bf16_f32 v132, v78, v79
	v_cvt_pk_bf16_f32 v133, v80, v81
	ds_write_b128 v0, v[130:133] offset:6912
	v_cvt_pk_bf16_f32 v130, v66, v67
	v_cvt_pk_bf16_f32 v131, v68, v69
	v_cvt_pk_bf16_f32 v132, v70, v71
	v_cvt_pk_bf16_f32 v133, v72, v73
	ds_write_b128 v0, v[130:133] offset:6976
	v_cvt_pk_bf16_f32 v130, v58, v59
	v_cvt_pk_bf16_f32 v131, v60, v61
	v_cvt_pk_bf16_f32 v132, v62, v63
	v_cvt_pk_bf16_f32 v133, v64, v65
	ds_write_b128 v0, v[130:133] offset:9216
	v_cvt_pk_bf16_f32 v130, v50, v51
	v_cvt_pk_bf16_f32 v131, v52, v53
	v_cvt_pk_bf16_f32 v132, v54, v55
	v_cvt_pk_bf16_f32 v133, v56, v57
	ds_write_b128 v0, v[130:133] offset:9280
	v_cvt_pk_bf16_f32 v130, v42, v43
	v_cvt_pk_bf16_f32 v131, v44, v45
	v_cvt_pk_bf16_f32 v132, v46, v47
	v_cvt_pk_bf16_f32 v133, v48, v49
	ds_write_b128 v0, v[130:133] offset:11520
	v_cvt_pk_bf16_f32 v130, v34, v35
	v_cvt_pk_bf16_f32 v131, v36, v37
	v_cvt_pk_bf16_f32 v132, v38, v39
	v_cvt_pk_bf16_f32 v133, v40, v41
	ds_write_b128 v0, v[130:133] offset:11584
	v_cvt_pk_bf16_f32 v130, v26, v27
	v_cvt_pk_bf16_f32 v131, v28, v29
	v_cvt_pk_bf16_f32 v132, v30, v31
	v_cvt_pk_bf16_f32 v133, v32, v33
	ds_write_b128 v0, v[130:133] offset:13824
	v_cvt_pk_bf16_f32 v130, v18, v19
	v_cvt_pk_bf16_f32 v131, v20, v21
	v_cvt_pk_bf16_f32 v132, v22, v23
	v_cvt_pk_bf16_f32 v133, v24, v25
	ds_write_b128 v0, v[130:133] offset:13888
	v_cvt_pk_bf16_f32 v130, v10, v11
	v_cvt_pk_bf16_f32 v131, v12, v13
	v_cvt_pk_bf16_f32 v132, v14, v15
	v_cvt_pk_bf16_f32 v133, v16, v17
	ds_write_b128 v0, v[130:133] offset:16128
	v_cvt_pk_bf16_f32 v130, v2, v3
	v_cvt_pk_bf16_f32 v131, v4, v5
	v_cvt_pk_bf16_f32 v132, v6, v7
	v_cvt_pk_bf16_f32 v133, v8, v9
	ds_write_b128 v0, v[130:133] offset:16192
	v_and_b32_e32 v0, 0xffffff80, v136
	v_add_u32_e32 v130, s48, v0
	v_ashrrev_i32_e32 v131, 31, v130
	v_lshlrev_b64 v[130:131], 11, v[130:131]
	v_lshl_add_u64 v[130:131], s[94:95], 0, v[130:131]
	s_mov_b32 s92, s46
	v_and_b32_e32 v0, 64, v136
	v_lshl_add_u64 v[130:131], s[92:93], 1, v[130:131]
	v_lshlrev_b32_e32 v0, 1, v0
	v_lshl_add_u64 v[138:139], v[130:131], 0, v[0:1]
	v_lshlrev_b32_e32 v0, 4, v136
	v_and_b32_e32 v0, 0x70, v0
	v_bfe_u32 v140, v136, 3, 3
	v_or_b32_e32 v130, v137, v0
	s_waitcnt lgkmcnt(0)
	v_mad_u32_u24 v137, v140, s4, v130
	ds_read_b128 v[66:69], v137
	ds_read_b128 v[70:73], v137 offset:1152
	ds_read_b128 v[74:77], v137 offset:2304
	ds_read_b128 v[78:81], v137 offset:3456
	ds_read_b128 v[82:85], v137 offset:4608
	ds_read_b128 v[86:89], v137 offset:5760
	ds_read_b128 v[90:93], v137 offset:6912
	ds_read_b128 v[94:97], v137 offset:8064
	ds_read_b128 v[98:101], v137 offset:9216
	ds_read_b128 v[102:105], v137 offset:10368
	ds_read_b128 v[106:109], v137 offset:11520
	ds_read_b128 v[110:113], v137 offset:12672
	ds_read_b128 v[114:117], v137 offset:13824
	ds_read_b128 v[118:121], v137 offset:14976
	ds_read_b128 v[122:125], v137 offset:16128
	ds_read_b128 v[126:129], v137 offset:17280
	v_lshl_add_u64 v[138:139], v[138:139], 0, v[0:1]
	s_mov_b64 s[4:5], 0x47ff800
	v_lshl_add_u64 v[138:139], v[138:139], 0, s[4:5]
	v_lshlrev_b32_e32 v0, 11, v140
	v_lshl_add_u64 v[140:141], v[138:139], 0, v[0:1]
	s_waitcnt lgkmcnt(15)
	global_store_dwordx4 v[140:141], v[66:69], off
	v_or_b32_e32 v140, 0x4000, v0
	v_mov_b32_e32 v141, v1
	v_lshl_add_u64 v[140:141], v[138:139], 0, v[140:141]
	s_movk_i32 s82, 0x1bff
	s_waitcnt lgkmcnt(14)
	global_store_dwordx4 v[140:141], v[70:73], off
	v_or_b32_e32 v140, 0x8000, v0
	v_mov_b32_e32 v141, v1
	v_lshl_add_u64 v[140:141], v[138:139], 0, v[140:141]
	s_waitcnt lgkmcnt(13)
	global_store_dwordx4 v[140:141], v[74:77], off
	v_or_b32_e32 v140, 0xc000, v0
	v_mov_b32_e32 v141, v1
	v_lshl_add_u64 v[140:141], v[138:139], 0, v[140:141]
	s_waitcnt lgkmcnt(12)
	global_store_dwordx4 v[140:141], v[78:81], off
	v_or_b32_e32 v140, 0x10000, v0
	v_mov_b32_e32 v141, v1
	v_lshl_add_u64 v[140:141], v[138:139], 0, v[140:141]
	s_waitcnt lgkmcnt(11)
	global_store_dwordx4 v[140:141], v[82:85], off
	v_or_b32_e32 v140, 0x14000, v0
	v_mov_b32_e32 v141, v1
	v_lshl_add_u64 v[140:141], v[138:139], 0, v[140:141]
	s_waitcnt lgkmcnt(10)
	global_store_dwordx4 v[140:141], v[86:89], off
	v_or_b32_e32 v140, 0x18000, v0
	v_mov_b32_e32 v141, v1
	v_lshl_add_u64 v[140:141], v[138:139], 0, v[140:141]
	s_waitcnt lgkmcnt(9)
	global_store_dwordx4 v[140:141], v[90:93], off
	v_or_b32_e32 v140, 0x1c000, v0
	v_mov_b32_e32 v141, v1
	v_lshl_add_u64 v[140:141], v[138:139], 0, v[140:141]
	s_waitcnt lgkmcnt(8)
	global_store_dwordx4 v[140:141], v[94:97], off
	v_or_b32_e32 v140, 0x20000, v0
	v_mov_b32_e32 v141, v1
	v_lshl_add_u64 v[140:141], v[138:139], 0, v[140:141]
	s_waitcnt lgkmcnt(7)
	global_store_dwordx4 v[140:141], v[98:101], off
	v_or_b32_e32 v140, 0x24000, v0
	v_mov_b32_e32 v141, v1
	v_lshl_add_u64 v[140:141], v[138:139], 0, v[140:141]
	s_waitcnt lgkmcnt(6)
	global_store_dwordx4 v[140:141], v[102:105], off
	v_or_b32_e32 v140, 0x28000, v0
	v_mov_b32_e32 v141, v1
	v_lshl_add_u64 v[140:141], v[138:139], 0, v[140:141]
	s_waitcnt lgkmcnt(5)
	global_store_dwordx4 v[140:141], v[106:109], off
	v_or_b32_e32 v140, 0x2c000, v0
	v_mov_b32_e32 v141, v1
	v_lshl_add_u64 v[140:141], v[138:139], 0, v[140:141]
	s_waitcnt lgkmcnt(4)
	global_store_dwordx4 v[140:141], v[110:113], off
	v_or_b32_e32 v140, 0x30000, v0
	v_mov_b32_e32 v141, v1
	v_lshl_add_u64 v[140:141], v[138:139], 0, v[140:141]
	s_waitcnt lgkmcnt(3)
	global_store_dwordx4 v[140:141], v[114:117], off
	v_or_b32_e32 v140, 0x34000, v0
	v_mov_b32_e32 v141, v1
	v_lshl_add_u64 v[140:141], v[138:139], 0, v[140:141]
	s_waitcnt lgkmcnt(2)
	global_store_dwordx4 v[140:141], v[118:121], off
	v_or_b32_e32 v140, 0x38000, v0
	v_mov_b32_e32 v141, v1
	v_lshl_add_u64 v[140:141], v[138:139], 0, v[140:141]
	v_or_b32_e32 v0, 0x3c000, v0
	s_waitcnt lgkmcnt(1)
	global_store_dwordx4 v[140:141], v[122:125], off
	v_lshl_add_u64 v[138:139], v[138:139], 0, v[0:1]
	s_waitcnt lgkmcnt(0)
	global_store_dwordx4 v[138:139], v[126:129], off
	s_waitcnt lgkmcnt(0)
	s_barrier

.LBB0_261:
	s_andn2_b64 vcc, exec, s[50:51]
	s_cbranch_vccnz .LBB0_263
	v_lshrrev_b32_e32 v0, 6, v136
	v_mul_lo_u32 v137, v0, s14
	v_and_b32_e32 v130, 15, v136
	v_and_or_b32 v0, v136, 48, v137
	s_movk_i32 s4, 0x90
	s_mov_b32 s6, 0x3e38aa3b
	v_mad_u32_u24 v0, v130, s4, v0
	v_pk_mul_f32 v[132:133], v[124:125], s[6:7] op_sel_hi:[1,0]
	v_pk_mul_f32 v[130:131], v[122:123], s[6:7] op_sel_hi:[1,0]
	v_pk_mul_f32 v[138:139], v[128:129], s[6:7] op_sel_hi:[1,0]
	v_pk_mul_f32 v[140:141], v[126:127], s[6:7] op_sel_hi:[1,0]
	v_cvt_pk_bf16_f32 v130, v130, v131
	v_cvt_pk_bf16_f32 v131, v132, v133
	v_cvt_pk_bf16_f32 v132, v140, v141
	v_cvt_pk_bf16_f32 v133, v138, v139
	s_waitcnt vmcnt(0)
	ds_write_b128 v0, v[130:133]
	v_pk_mul_f32 v[132:133], v[116:117], s[6:7] op_sel_hi:[1,0]
	v_pk_mul_f32 v[130:131], v[114:115], s[6:7] op_sel_hi:[1,0]
	v_pk_mul_f32 v[138:139], v[120:121], s[6:7] op_sel_hi:[1,0]
	v_pk_mul_f32 v[140:141], v[118:119], s[6:7] op_sel_hi:[1,0]
	v_cvt_pk_bf16_f32 v130, v130, v131
	v_cvt_pk_bf16_f32 v131, v132, v133
	v_cvt_pk_bf16_f32 v132, v140, v141
	v_cvt_pk_bf16_f32 v133, v138, v139
	ds_write_b128 v0, v[130:133] offset:64
	v_pk_mul_f32 v[132:133], v[108:109], s[6:7] op_sel_hi:[1,0]
	v_pk_mul_f32 v[130:131], v[106:107], s[6:7] op_sel_hi:[1,0]
	v_pk_mul_f32 v[138:139], v[112:113], s[6:7] op_sel_hi:[1,0]
	v_pk_mul_f32 v[140:141], v[110:111], s[6:7] op_sel_hi:[1,0]
	v_cvt_pk_bf16_f32 v130, v130, v131
	v_cvt_pk_bf16_f32 v131, v132, v133
	v_cvt_pk_bf16_f32 v132, v140, v141
	v_cvt_pk_bf16_f32 v133, v138, v139
	ds_write_b128 v0, v[130:133] offset:2304
	v_pk_mul_f32 v[132:133], v[100:101], s[6:7] op_sel_hi:[1,0]
	v_pk_mul_f32 v[130:131], v[98:99], s[6:7] op_sel_hi:[1,0]
	v_pk_mul_f32 v[138:139], v[104:105], s[6:7] op_sel_hi:[1,0]
	v_pk_mul_f32 v[140:141], v[102:103], s[6:7] op_sel_hi:[1,0]
	v_cvt_pk_bf16_f32 v130, v130, v131
	v_cvt_pk_bf16_f32 v131, v132, v133
	v_cvt_pk_bf16_f32 v132, v140, v141
	v_cvt_pk_bf16_f32 v133, v138, v139
	ds_write_b128 v0, v[130:133] offset:2368
	v_pk_mul_f32 v[132:133], v[92:93], s[6:7] op_sel_hi:[1,0]
	v_pk_mul_f32 v[130:131], v[90:91], s[6:7] op_sel_hi:[1,0]
	v_pk_mul_f32 v[138:139], v[96:97], s[6:7] op_sel_hi:[1,0]
	v_pk_mul_f32 v[140:141], v[94:95], s[6:7] op_sel_hi:[1,0]
	v_cvt_pk_bf16_f32 v130, v130, v131
	v_cvt_pk_bf16_f32 v131, v132, v133
	v_cvt_pk_bf16_f32 v132, v140, v141
	v_cvt_pk_bf16_f32 v133, v138, v139
	ds_write_b128 v0, v[130:133] offset:4608
	v_pk_mul_f32 v[132:133], v[84:85], s[6:7] op_sel_hi:[1,0]
	v_pk_mul_f32 v[130:131], v[82:83], s[6:7] op_sel_hi:[1,0]
	v_pk_mul_f32 v[138:139], v[88:89], s[6:7] op_sel_hi:[1,0]
	v_pk_mul_f32 v[140:141], v[86:87], s[6:7] op_sel_hi:[1,0]
	v_cvt_pk_bf16_f32 v130, v130, v131
	v_cvt_pk_bf16_f32 v131, v132, v133
	v_cvt_pk_bf16_f32 v132, v140, v141
	v_cvt_pk_bf16_f32 v133, v138, v139
	ds_write_b128 v0, v[130:133] offset:4672
	v_pk_mul_f32 v[132:133], v[76:77], s[6:7] op_sel_hi:[1,0]
	v_pk_mul_f32 v[130:131], v[74:75], s[6:7] op_sel_hi:[1,0]
	v_pk_mul_f32 v[138:139], v[80:81], s[6:7] op_sel_hi:[1,0]
	v_pk_mul_f32 v[140:141], v[78:79], s[6:7] op_sel_hi:[1,0]
	v_cvt_pk_bf16_f32 v130, v130, v131
	v_cvt_pk_bf16_f32 v131, v132, v133
	v_cvt_pk_bf16_f32 v132, v140, v141
	v_cvt_pk_bf16_f32 v133, v138, v139
	ds_write_b128 v0, v[130:133] offset:6912
	v_pk_mul_f32 v[132:133], v[68:69], s[6:7] op_sel_hi:[1,0]
	v_pk_mul_f32 v[130:131], v[66:67], s[6:7] op_sel_hi:[1,0]
	v_pk_mul_f32 v[138:139], v[72:73], s[6:7] op_sel_hi:[1,0]
	v_pk_mul_f32 v[140:141], v[70:71], s[6:7] op_sel_hi:[1,0]
	v_cvt_pk_bf16_f32 v130, v130, v131
	v_cvt_pk_bf16_f32 v131, v132, v133
	v_cvt_pk_bf16_f32 v132, v140, v141
	v_cvt_pk_bf16_f32 v133, v138, v139
	ds_write_b128 v0, v[130:133] offset:6976
	v_pk_mul_f32 v[132:133], v[60:61], s[6:7] op_sel_hi:[1,0]
	v_pk_mul_f32 v[130:131], v[58:59], s[6:7] op_sel_hi:[1,0]
	v_pk_mul_f32 v[138:139], v[64:65], s[6:7] op_sel_hi:[1,0]
	v_pk_mul_f32 v[140:141], v[62:63], s[6:7] op_sel_hi:[1,0]
	v_cvt_pk_bf16_f32 v130, v130, v131
	v_cvt_pk_bf16_f32 v131, v132, v133
	v_cvt_pk_bf16_f32 v132, v140, v141
	v_cvt_pk_bf16_f32 v133, v138, v139
	ds_write_b128 v0, v[130:133] offset:9216
	v_pk_mul_f32 v[132:133], v[52:53], s[6:7] op_sel_hi:[1,0]
	v_pk_mul_f32 v[130:131], v[50:51], s[6:7] op_sel_hi:[1,0]
	v_pk_mul_f32 v[138:139], v[56:57], s[6:7] op_sel_hi:[1,0]
	v_pk_mul_f32 v[140:141], v[54:55], s[6:7] op_sel_hi:[1,0]
	v_cvt_pk_bf16_f32 v130, v130, v131
	v_cvt_pk_bf16_f32 v131, v132, v133
	v_cvt_pk_bf16_f32 v132, v140, v141
	v_cvt_pk_bf16_f32 v133, v138, v139
	ds_write_b128 v0, v[130:133] offset:9280
	v_pk_mul_f32 v[132:133], v[44:45], s[6:7] op_sel_hi:[1,0]
	v_pk_mul_f32 v[130:131], v[42:43], s[6:7] op_sel_hi:[1,0]
	v_pk_mul_f32 v[138:139], v[48:49], s[6:7] op_sel_hi:[1,0]
	v_pk_mul_f32 v[140:141], v[46:47], s[6:7] op_sel_hi:[1,0]
	v_cvt_pk_bf16_f32 v130, v130, v131
	v_cvt_pk_bf16_f32 v131, v132, v133
	v_cvt_pk_bf16_f32 v132, v140, v141
	v_cvt_pk_bf16_f32 v133, v138, v139
	ds_write_b128 v0, v[130:133] offset:11520
	v_pk_mul_f32 v[132:133], v[36:37], s[6:7] op_sel_hi:[1,0]
	v_pk_mul_f32 v[130:131], v[34:35], s[6:7] op_sel_hi:[1,0]
	v_pk_mul_f32 v[138:139], v[40:41], s[6:7] op_sel_hi:[1,0]
	v_pk_mul_f32 v[140:141], v[38:39], s[6:7] op_sel_hi:[1,0]
	v_cvt_pk_bf16_f32 v130, v130, v131
	v_cvt_pk_bf16_f32 v131, v132, v133
	v_cvt_pk_bf16_f32 v132, v140, v141
	v_cvt_pk_bf16_f32 v133, v138, v139
	ds_write_b128 v0, v[130:133] offset:11584
	v_pk_mul_f32 v[132:133], v[28:29], s[6:7] op_sel_hi:[1,0]
	v_pk_mul_f32 v[130:131], v[26:27], s[6:7] op_sel_hi:[1,0]
	v_pk_mul_f32 v[138:139], v[32:33], s[6:7] op_sel_hi:[1,0]
	v_pk_mul_f32 v[140:141], v[30:31], s[6:7] op_sel_hi:[1,0]
	v_cvt_pk_bf16_f32 v130, v130, v131
	v_cvt_pk_bf16_f32 v131, v132, v133
	v_cvt_pk_bf16_f32 v132, v140, v141
	v_cvt_pk_bf16_f32 v133, v138, v139
	ds_write_b128 v0, v[130:133] offset:13824
	v_pk_mul_f32 v[132:133], v[20:21], s[6:7] op_sel_hi:[1,0]
	v_pk_mul_f32 v[130:131], v[18:19], s[6:7] op_sel_hi:[1,0]
	v_pk_mul_f32 v[138:139], v[24:25], s[6:7] op_sel_hi:[1,0]
	v_pk_mul_f32 v[140:141], v[22:23], s[6:7] op_sel_hi:[1,0]
	v_cvt_pk_bf16_f32 v130, v130, v131
	v_cvt_pk_bf16_f32 v131, v132, v133
	v_cvt_pk_bf16_f32 v132, v140, v141
	v_cvt_pk_bf16_f32 v133, v138, v139
	ds_write_b128 v0, v[130:133] offset:13888
	v_pk_mul_f32 v[132:133], v[12:13], s[6:7] op_sel_hi:[1,0]
	v_pk_mul_f32 v[130:131], v[10:11], s[6:7] op_sel_hi:[1,0]
	v_pk_mul_f32 v[138:139], v[16:17], s[6:7] op_sel_hi:[1,0]
	v_pk_mul_f32 v[140:141], v[14:15], s[6:7] op_sel_hi:[1,0]
	v_cvt_pk_bf16_f32 v130, v130, v131
	v_cvt_pk_bf16_f32 v131, v132, v133
	v_cvt_pk_bf16_f32 v132, v140, v141
	v_cvt_pk_bf16_f32 v133, v138, v139
	ds_write_b128 v0, v[130:133] offset:16128
	v_pk_mul_f32 v[132:133], v[4:5], s[6:7] op_sel_hi:[1,0]
	v_pk_mul_f32 v[130:131], v[2:3], s[6:7] op_sel_hi:[1,0]
	v_pk_mul_f32 v[138:139], v[8:9], s[6:7] op_sel_hi:[1,0]
	v_pk_mul_f32 v[140:141], v[6:7], s[6:7] op_sel_hi:[1,0]
	v_cvt_pk_bf16_f32 v130, v130, v131
	v_cvt_pk_bf16_f32 v131, v132, v133
	v_cvt_pk_bf16_f32 v132, v140, v141
	v_cvt_pk_bf16_f32 v133, v138, v139
	ds_write_b128 v0, v[130:133] offset:16192
	v_and_b32_e32 v0, 0xffffff80, v136
	v_add_u32_e32 v130, s48, v0
	v_ashrrev_i32_e32 v131, 31, v130
	v_lshlrev_b64 v[130:131], 11, v[130:131]
	v_lshl_add_u64 v[130:131], s[42:43], 0, v[130:131]
	v_and_b32_e32 v0, 64, v136
	v_lshl_add_u64 v[130:131], s[46:47], 1, v[130:131]
	v_lshlrev_b32_e32 v0, 1, v0
	v_lshl_add_u64 v[138:139], v[130:131], 0, v[0:1]
	v_lshlrev_b32_e32 v0, 4, v136
	v_and_b32_e32 v0, 0x70, v0
	v_bfe_u32 v140, v136, 3, 3
	v_or_b32_e32 v130, v137, v0
	s_waitcnt lgkmcnt(0)
	v_mad_u32_u24 v137, v140, s4, v130
	ds_read_b128 v[66:69], v137
	ds_read_b128 v[70:73], v137 offset:1152
	ds_read_b128 v[74:77], v137 offset:2304
	ds_read_b128 v[78:81], v137 offset:3456
	ds_read_b128 v[82:85], v137 offset:4608
	ds_read_b128 v[86:89], v137 offset:5760
	ds_read_b128 v[90:93], v137 offset:6912
	ds_read_b128 v[94:97], v137 offset:8064
	ds_read_b128 v[98:101], v137 offset:9216
	ds_read_b128 v[102:105], v137 offset:10368
	ds_read_b128 v[106:109], v137 offset:11520
	ds_read_b128 v[110:113], v137 offset:12672
	ds_read_b128 v[114:117], v137 offset:13824
	ds_read_b128 v[118:121], v137 offset:14976
	ds_read_b128 v[122:125], v137 offset:16128
	ds_read_b128 v[126:129], v137 offset:17280
	v_lshl_add_u64 v[138:139], v[138:139], 0, v[0:1]
	v_lshlrev_b32_e32 v0, 11, v140
	v_lshl_add_u64 v[140:141], v[138:139], 0, v[0:1]
	s_waitcnt lgkmcnt(15)
	global_store_dwordx4 v[140:141], v[66:69], off
	v_or_b32_e32 v140, 0x4000, v0
	v_mov_b32_e32 v141, v1
	v_lshl_add_u64 v[140:141], v[138:139], 0, v[140:141]
	s_waitcnt lgkmcnt(14)
	global_store_dwordx4 v[140:141], v[70:73], off
	v_or_b32_e32 v140, 0x8000, v0
	v_mov_b32_e32 v141, v1
	v_lshl_add_u64 v[140:141], v[138:139], 0, v[140:141]
	s_waitcnt lgkmcnt(13)
	global_store_dwordx4 v[140:141], v[74:77], off
	v_or_b32_e32 v140, 0xc000, v0
	v_mov_b32_e32 v141, v1
	v_lshl_add_u64 v[140:141], v[138:139], 0, v[140:141]
	s_waitcnt lgkmcnt(12)
	global_store_dwordx4 v[140:141], v[78:81], off
	v_or_b32_e32 v140, 0x10000, v0
	v_mov_b32_e32 v141, v1
	v_lshl_add_u64 v[140:141], v[138:139], 0, v[140:141]
	s_waitcnt lgkmcnt(11)
	global_store_dwordx4 v[140:141], v[82:85], off
	v_or_b32_e32 v140, 0x14000, v0
	v_mov_b32_e32 v141, v1
	v_lshl_add_u64 v[140:141], v[138:139], 0, v[140:141]
	s_waitcnt lgkmcnt(10)
	global_store_dwordx4 v[140:141], v[86:89], off
	v_or_b32_e32 v140, 0x18000, v0
	v_mov_b32_e32 v141, v1
	v_lshl_add_u64 v[140:141], v[138:139], 0, v[140:141]
	s_waitcnt lgkmcnt(9)
	global_store_dwordx4 v[140:141], v[90:93], off
	v_or_b32_e32 v140, 0x1c000, v0
	v_mov_b32_e32 v141, v1
	v_lshl_add_u64 v[140:141], v[138:139], 0, v[140:141]
	s_waitcnt lgkmcnt(8)
	global_store_dwordx4 v[140:141], v[94:97], off
	v_or_b32_e32 v140, 0x20000, v0
	v_mov_b32_e32 v141, v1
	v_lshl_add_u64 v[140:141], v[138:139], 0, v[140:141]
	s_waitcnt lgkmcnt(7)
	global_store_dwordx4 v[140:141], v[98:101], off
	v_or_b32_e32 v140, 0x24000, v0
	v_mov_b32_e32 v141, v1
	v_lshl_add_u64 v[140:141], v[138:139], 0, v[140:141]
	s_waitcnt lgkmcnt(6)
	global_store_dwordx4 v[140:141], v[102:105], off
	v_or_b32_e32 v140, 0x28000, v0
	v_mov_b32_e32 v141, v1
	v_lshl_add_u64 v[140:141], v[138:139], 0, v[140:141]
	s_waitcnt lgkmcnt(5)
	global_store_dwordx4 v[140:141], v[106:109], off
	v_or_b32_e32 v140, 0x2c000, v0
	v_mov_b32_e32 v141, v1
	v_lshl_add_u64 v[140:141], v[138:139], 0, v[140:141]
	s_waitcnt lgkmcnt(4)
	global_store_dwordx4 v[140:141], v[110:113], off
	v_or_b32_e32 v140, 0x30000, v0
	v_mov_b32_e32 v141, v1
	v_lshl_add_u64 v[140:141], v[138:139], 0, v[140:141]
	s_waitcnt lgkmcnt(3)
	global_store_dwordx4 v[140:141], v[114:117], off
	v_or_b32_e32 v140, 0x34000, v0
	v_mov_b32_e32 v141, v1
	v_lshl_add_u64 v[140:141], v[138:139], 0, v[140:141]
	s_waitcnt lgkmcnt(2)
	global_store_dwordx4 v[140:141], v[118:121], off
	v_or_b32_e32 v140, 0x38000, v0
	v_mov_b32_e32 v141, v1
	v_lshl_add_u64 v[140:141], v[138:139], 0, v[140:141]
	v_or_b32_e32 v0, 0x3c000, v0
	s_waitcnt lgkmcnt(1)
	global_store_dwordx4 v[140:141], v[122:125], off
	v_lshl_add_u64 v[138:139], v[138:139], 0, v[0:1]
	s_waitcnt lgkmcnt(0)
	global_store_dwordx4 v[138:139], v[126:129], off
	s_waitcnt lgkmcnt(0)
	s_barrier

.LBB0_271:
	s_andn2_b64 vcc, exec, s[50:51]
	s_cbranch_vccnz .LBB0_273
	v_lshrrev_b32_e32 v0, 6, v136
	v_mul_lo_u32 v137, v0, s14
	v_and_b32_e32 v130, 15, v136
	v_and_or_b32 v0, v136, 48, v137
	s_movk_i32 s4, 0x90
	v_mad_u32_u24 v0, v130, s4, v0
	v_cvt_pk_bf16_f32 v130, v122, v123
	v_cvt_pk_bf16_f32 v131, v124, v125
	v_cvt_pk_bf16_f32 v132, v126, v127
	v_cvt_pk_bf16_f32 v133, v128, v129
	s_waitcnt vmcnt(0)
	ds_write_b128 v0, v[130:133]
	v_cvt_pk_bf16_f32 v130, v114, v115
	v_cvt_pk_bf16_f32 v131, v116, v117
	v_cvt_pk_bf16_f32 v132, v118, v119
	v_cvt_pk_bf16_f32 v133, v120, v121
	ds_write_b128 v0, v[130:133] offset:64
	v_cvt_pk_bf16_f32 v130, v106, v107
	v_cvt_pk_bf16_f32 v131, v108, v109
	v_cvt_pk_bf16_f32 v132, v110, v111
	v_cvt_pk_bf16_f32 v133, v112, v113
	ds_write_b128 v0, v[130:133] offset:2304
	v_cvt_pk_bf16_f32 v130, v98, v99
	v_cvt_pk_bf16_f32 v131, v100, v101
	v_cvt_pk_bf16_f32 v132, v102, v103
	v_cvt_pk_bf16_f32 v133, v104, v105
	ds_write_b128 v0, v[130:133] offset:2368
	v_cvt_pk_bf16_f32 v130, v90, v91
	v_cvt_pk_bf16_f32 v131, v92, v93
	v_cvt_pk_bf16_f32 v132, v94, v95
	v_cvt_pk_bf16_f32 v133, v96, v97
	ds_write_b128 v0, v[130:133] offset:4608
	v_cvt_pk_bf16_f32 v130, v82, v83
	v_cvt_pk_bf16_f32 v131, v84, v85
	v_cvt_pk_bf16_f32 v132, v86, v87
	v_cvt_pk_bf16_f32 v133, v88, v89
	ds_write_b128 v0, v[130:133] offset:4672
	v_cvt_pk_bf16_f32 v130, v74, v75
	v_cvt_pk_bf16_f32 v131, v76, v77
	v_cvt_pk_bf16_f32 v132, v78, v79
	v_cvt_pk_bf16_f32 v133, v80, v81
	ds_write_b128 v0, v[130:133] offset:6912
	v_cvt_pk_bf16_f32 v130, v66, v67
	v_cvt_pk_bf16_f32 v131, v68, v69
	v_cvt_pk_bf16_f32 v132, v70, v71
	v_cvt_pk_bf16_f32 v133, v72, v73
	ds_write_b128 v0, v[130:133] offset:6976
	v_cvt_pk_bf16_f32 v130, v58, v59
	v_cvt_pk_bf16_f32 v131, v60, v61
	v_cvt_pk_bf16_f32 v132, v62, v63
	v_cvt_pk_bf16_f32 v133, v64, v65
	ds_write_b128 v0, v[130:133] offset:9216
	v_cvt_pk_bf16_f32 v130, v50, v51
	v_cvt_pk_bf16_f32 v131, v52, v53
	v_cvt_pk_bf16_f32 v132, v54, v55
	v_cvt_pk_bf16_f32 v133, v56, v57
	ds_write_b128 v0, v[130:133] offset:9280
	v_cvt_pk_bf16_f32 v130, v42, v43
	v_cvt_pk_bf16_f32 v131, v44, v45
	v_cvt_pk_bf16_f32 v132, v46, v47
	v_cvt_pk_bf16_f32 v133, v48, v49
	ds_write_b128 v0, v[130:133] offset:11520
	v_cvt_pk_bf16_f32 v130, v34, v35
	v_cvt_pk_bf16_f32 v131, v36, v37
	v_cvt_pk_bf16_f32 v132, v38, v39
	v_cvt_pk_bf16_f32 v133, v40, v41
	ds_write_b128 v0, v[130:133] offset:11584
	v_cvt_pk_bf16_f32 v130, v26, v27
	v_cvt_pk_bf16_f32 v131, v28, v29
	v_cvt_pk_bf16_f32 v132, v30, v31
	v_cvt_pk_bf16_f32 v133, v32, v33
	ds_write_b128 v0, v[130:133] offset:13824
	v_cvt_pk_bf16_f32 v130, v18, v19
	v_cvt_pk_bf16_f32 v131, v20, v21
	v_cvt_pk_bf16_f32 v132, v22, v23
	v_cvt_pk_bf16_f32 v133, v24, v25
	ds_write_b128 v0, v[130:133] offset:13888
	v_cvt_pk_bf16_f32 v130, v10, v11
	v_cvt_pk_bf16_f32 v131, v12, v13
	v_cvt_pk_bf16_f32 v132, v14, v15
	v_cvt_pk_bf16_f32 v133, v16, v17
	ds_write_b128 v0, v[130:133] offset:16128
	v_cvt_pk_bf16_f32 v130, v2, v3
	v_cvt_pk_bf16_f32 v131, v4, v5
	v_cvt_pk_bf16_f32 v132, v6, v7
	v_cvt_pk_bf16_f32 v133, v8, v9
	ds_write_b128 v0, v[130:133] offset:16192
	v_and_b32_e32 v0, 0xffffff80, v136
	v_add_u32_e32 v130, s48, v0
	v_ashrrev_i32_e32 v131, 31, v130
	v_lshlrev_b64 v[130:131], 11, v[130:131]
	v_lshl_add_u64 v[130:131], s[94:95], 0, v[130:131]
	s_mov_b32 s92, s46
	v_and_b32_e32 v0, 64, v136
	v_lshl_add_u64 v[130:131], s[92:93], 1, v[130:131]
	v_lshlrev_b32_e32 v0, 1, v0
	v_lshl_add_u64 v[138:139], v[130:131], 0, v[0:1]
	v_lshlrev_b32_e32 v0, 4, v136
	v_and_b32_e32 v0, 0x70, v0
	v_bfe_u32 v140, v136, 3, 3
	v_or_b32_e32 v130, v137, v0
	s_waitcnt lgkmcnt(0)
	v_mad_u32_u24 v137, v140, s4, v130
	ds_read_b128 v[66:69], v137
	ds_read_b128 v[70:73], v137 offset:1152
	ds_read_b128 v[74:77], v137 offset:2304
	ds_read_b128 v[78:81], v137 offset:3456
	ds_read_b128 v[82:85], v137 offset:4608
	ds_read_b128 v[86:89], v137 offset:5760
	ds_read_b128 v[90:93], v137 offset:6912
	ds_read_b128 v[94:97], v137 offset:8064
	ds_read_b128 v[98:101], v137 offset:9216
	ds_read_b128 v[102:105], v137 offset:10368
	ds_read_b128 v[106:109], v137 offset:11520
	ds_read_b128 v[110:113], v137 offset:12672
	ds_read_b128 v[114:117], v137 offset:13824
	ds_read_b128 v[118:121], v137 offset:14976
	ds_read_b128 v[122:125], v137 offset:16128
	ds_read_b128 v[126:129], v137 offset:17280
	v_lshl_add_u64 v[138:139], v[138:139], 0, v[0:1]
	s_mov_b64 s[4:5], 0x8fff000
	v_lshl_add_u64 v[138:139], v[138:139], 0, s[4:5]
	v_lshlrev_b32_e32 v0, 11, v140
	v_lshl_add_u64 v[140:141], v[138:139], 0, v[0:1]
	s_waitcnt lgkmcnt(15)
	global_store_dwordx4 v[140:141], v[66:69], off
	v_or_b32_e32 v140, 0x4000, v0
	v_mov_b32_e32 v141, v1
	v_lshl_add_u64 v[140:141], v[138:139], 0, v[140:141]
	s_movk_i32 s82, 0x1bff
	s_waitcnt lgkmcnt(14)
	global_store_dwordx4 v[140:141], v[70:73], off
	v_or_b32_e32 v140, 0x8000, v0
	v_mov_b32_e32 v141, v1
	v_lshl_add_u64 v[140:141], v[138:139], 0, v[140:141]
	s_waitcnt lgkmcnt(13)
	global_store_dwordx4 v[140:141], v[74:77], off
	v_or_b32_e32 v140, 0xc000, v0
	v_mov_b32_e32 v141, v1
	v_lshl_add_u64 v[140:141], v[138:139], 0, v[140:141]
	s_waitcnt lgkmcnt(12)
	global_store_dwordx4 v[140:141], v[78:81], off
	v_or_b32_e32 v140, 0x10000, v0
	v_mov_b32_e32 v141, v1
	v_lshl_add_u64 v[140:141], v[138:139], 0, v[140:141]
	s_waitcnt lgkmcnt(11)
	global_store_dwordx4 v[140:141], v[82:85], off
	v_or_b32_e32 v140, 0x14000, v0
	v_mov_b32_e32 v141, v1
	v_lshl_add_u64 v[140:141], v[138:139], 0, v[140:141]
	s_waitcnt lgkmcnt(10)
	global_store_dwordx4 v[140:141], v[86:89], off
	v_or_b32_e32 v140, 0x18000, v0
	v_mov_b32_e32 v141, v1
	v_lshl_add_u64 v[140:141], v[138:139], 0, v[140:141]
	s_waitcnt lgkmcnt(9)
	global_store_dwordx4 v[140:141], v[90:93], off
	v_or_b32_e32 v140, 0x1c000, v0
	v_mov_b32_e32 v141, v1
	v_lshl_add_u64 v[140:141], v[138:139], 0, v[140:141]
	s_waitcnt lgkmcnt(8)
	global_store_dwordx4 v[140:141], v[94:97], off
	v_or_b32_e32 v140, 0x20000, v0
	v_mov_b32_e32 v141, v1
	v_lshl_add_u64 v[140:141], v[138:139], 0, v[140:141]
	s_waitcnt lgkmcnt(7)
	global_store_dwordx4 v[140:141], v[98:101], off
	v_or_b32_e32 v140, 0x24000, v0
	v_mov_b32_e32 v141, v1
	v_lshl_add_u64 v[140:141], v[138:139], 0, v[140:141]
	s_waitcnt lgkmcnt(6)
	global_store_dwordx4 v[140:141], v[102:105], off
	v_or_b32_e32 v140, 0x28000, v0
	v_mov_b32_e32 v141, v1
	v_lshl_add_u64 v[140:141], v[138:139], 0, v[140:141]
	s_waitcnt lgkmcnt(5)
	global_store_dwordx4 v[140:141], v[106:109], off
	v_or_b32_e32 v140, 0x2c000, v0
	v_mov_b32_e32 v141, v1
	v_lshl_add_u64 v[140:141], v[138:139], 0, v[140:141]
	s_waitcnt lgkmcnt(4)
	global_store_dwordx4 v[140:141], v[110:113], off
	v_or_b32_e32 v140, 0x30000, v0
	v_mov_b32_e32 v141, v1
	v_lshl_add_u64 v[140:141], v[138:139], 0, v[140:141]
	s_waitcnt lgkmcnt(3)
	global_store_dwordx4 v[140:141], v[114:117], off
	v_or_b32_e32 v140, 0x34000, v0
	v_mov_b32_e32 v141, v1
	v_lshl_add_u64 v[140:141], v[138:139], 0, v[140:141]
	s_waitcnt lgkmcnt(2)
	global_store_dwordx4 v[140:141], v[118:121], off
	v_or_b32_e32 v140, 0x38000, v0
	v_mov_b32_e32 v141, v1
	v_lshl_add_u64 v[140:141], v[138:139], 0, v[140:141]
	v_or_b32_e32 v0, 0x3c000, v0
	s_waitcnt lgkmcnt(1)
	global_store_dwordx4 v[140:141], v[122:125], off
	v_lshl_add_u64 v[138:139], v[138:139], 0, v[0:1]
	s_waitcnt lgkmcnt(0)
	global_store_dwordx4 v[138:139], v[126:129], off
	s_waitcnt lgkmcnt(0)
	s_barrier

.LBB0_277:
	s_andn2_b64 vcc, exec, s[50:51]
	s_cbranch_vccnz .LBB0_236
	s_cmp_lt_i32 s80, 4
	s_cselect_b64 vcc, -1, 0
	v_mov_b32_e32 v0, 0x3db504f3
	v_lshrrev_b32_e32 v130, 6, v136
	v_cndmask_b32_e32 v0, 1.0, v0, vcc
	v_mul_lo_u32 v130, v130, s14
	v_and_b32_e32 v131, 15, v136
	v_and_or_b32 v132, v136, 48, v130
	s_movk_i32 s4, 0x90
	v_pk_mul_f32 v[4:5], v[0:1], v[4:5] op_sel_hi:[0,1]
	v_pk_mul_f32 v[2:3], v[0:1], v[2:3] op_sel_hi:[0,1]
	v_pk_mul_f32 v[8:9], v[0:1], v[8:9] op_sel_hi:[0,1]
	v_pk_mul_f32 v[6:7], v[0:1], v[6:7] op_sel_hi:[0,1]
	v_mad_u32_u24 v131, v131, s4, v132
	v_pk_mul_f32 v[124:125], v[0:1], v[124:125] op_sel_hi:[0,1]
	v_pk_mul_f32 v[122:123], v[0:1], v[122:123] op_sel_hi:[0,1]
	v_pk_mul_f32 v[128:129], v[0:1], v[128:129] op_sel_hi:[0,1]
	v_pk_mul_f32 v[126:127], v[0:1], v[126:127] op_sel_hi:[0,1]
	v_pk_mul_f32 v[116:117], v[0:1], v[116:117] op_sel_hi:[0,1]
	v_pk_mul_f32 v[114:115], v[0:1], v[114:115] op_sel_hi:[0,1]
	v_pk_mul_f32 v[120:121], v[0:1], v[120:121] op_sel_hi:[0,1]
	v_pk_mul_f32 v[118:119], v[0:1], v[118:119] op_sel_hi:[0,1]
	v_pk_mul_f32 v[108:109], v[0:1], v[108:109] op_sel_hi:[0,1]
	v_pk_mul_f32 v[106:107], v[0:1], v[106:107] op_sel_hi:[0,1]
	v_pk_mul_f32 v[112:113], v[0:1], v[112:113] op_sel_hi:[0,1]
	v_pk_mul_f32 v[110:111], v[0:1], v[110:111] op_sel_hi:[0,1]
	v_pk_mul_f32 v[100:101], v[0:1], v[100:101] op_sel_hi:[0,1]
	v_pk_mul_f32 v[98:99], v[0:1], v[98:99] op_sel_hi:[0,1]
	v_pk_mul_f32 v[104:105], v[0:1], v[104:105] op_sel_hi:[0,1]
	v_pk_mul_f32 v[102:103], v[0:1], v[102:103] op_sel_hi:[0,1]
	v_pk_mul_f32 v[92:93], v[0:1], v[92:93] op_sel_hi:[0,1]
	v_pk_mul_f32 v[90:91], v[0:1], v[90:91] op_sel_hi:[0,1]
	v_pk_mul_f32 v[96:97], v[0:1], v[96:97] op_sel_hi:[0,1]
	v_pk_mul_f32 v[94:95], v[0:1], v[94:95] op_sel_hi:[0,1]
	v_pk_mul_f32 v[84:85], v[0:1], v[84:85] op_sel_hi:[0,1]
	v_pk_mul_f32 v[82:83], v[0:1], v[82:83] op_sel_hi:[0,1]
	v_pk_mul_f32 v[88:89], v[0:1], v[88:89] op_sel_hi:[0,1]
	v_pk_mul_f32 v[86:87], v[0:1], v[86:87] op_sel_hi:[0,1]
	v_pk_mul_f32 v[76:77], v[0:1], v[76:77] op_sel_hi:[0,1]
	v_pk_mul_f32 v[74:75], v[0:1], v[74:75] op_sel_hi:[0,1]
	v_pk_mul_f32 v[80:81], v[0:1], v[80:81] op_sel_hi:[0,1]
	v_pk_mul_f32 v[78:79], v[0:1], v[78:79] op_sel_hi:[0,1]
	v_pk_mul_f32 v[68:69], v[0:1], v[68:69] op_sel_hi:[0,1]
	v_pk_mul_f32 v[66:67], v[0:1], v[66:67] op_sel_hi:[0,1]
	v_pk_mul_f32 v[72:73], v[0:1], v[72:73] op_sel_hi:[0,1]
	v_pk_mul_f32 v[70:71], v[0:1], v[70:71] op_sel_hi:[0,1]
	v_pk_mul_f32 v[60:61], v[0:1], v[60:61] op_sel_hi:[0,1]
	v_pk_mul_f32 v[58:59], v[0:1], v[58:59] op_sel_hi:[0,1]
	v_pk_mul_f32 v[64:65], v[0:1], v[64:65] op_sel_hi:[0,1]
	v_pk_mul_f32 v[62:63], v[0:1], v[62:63] op_sel_hi:[0,1]
	v_pk_mul_f32 v[52:53], v[0:1], v[52:53] op_sel_hi:[0,1]
	v_pk_mul_f32 v[50:51], v[0:1], v[50:51] op_sel_hi:[0,1]
	v_pk_mul_f32 v[56:57], v[0:1], v[56:57] op_sel_hi:[0,1]
	v_pk_mul_f32 v[54:55], v[0:1], v[54:55] op_sel_hi:[0,1]
	v_pk_mul_f32 v[44:45], v[0:1], v[44:45] op_sel_hi:[0,1]
	v_pk_mul_f32 v[42:43], v[0:1], v[42:43] op_sel_hi:[0,1]
	v_pk_mul_f32 v[48:49], v[0:1], v[48:49] op_sel_hi:[0,1]
	v_pk_mul_f32 v[46:47], v[0:1], v[46:47] op_sel_hi:[0,1]
	v_pk_mul_f32 v[36:37], v[0:1], v[36:37] op_sel_hi:[0,1]
	v_pk_mul_f32 v[34:35], v[0:1], v[34:35] op_sel_hi:[0,1]
	v_pk_mul_f32 v[40:41], v[0:1], v[40:41] op_sel_hi:[0,1]
	v_pk_mul_f32 v[38:39], v[0:1], v[38:39] op_sel_hi:[0,1]
	v_pk_mul_f32 v[28:29], v[0:1], v[28:29] op_sel_hi:[0,1]
	v_pk_mul_f32 v[26:27], v[0:1], v[26:27] op_sel_hi:[0,1]
	v_pk_mul_f32 v[32:33], v[0:1], v[32:33] op_sel_hi:[0,1]
	v_pk_mul_f32 v[30:31], v[0:1], v[30:31] op_sel_hi:[0,1]
	v_pk_mul_f32 v[20:21], v[0:1], v[20:21] op_sel_hi:[0,1]
	v_pk_mul_f32 v[18:19], v[0:1], v[18:19] op_sel_hi:[0,1]
	v_pk_mul_f32 v[24:25], v[0:1], v[24:25] op_sel_hi:[0,1]
	v_pk_mul_f32 v[22:23], v[0:1], v[22:23] op_sel_hi:[0,1]
	v_pk_mul_f32 v[12:13], v[0:1], v[12:13] op_sel_hi:[0,1]
	v_pk_mul_f32 v[10:11], v[0:1], v[10:11] op_sel_hi:[0,1]
	v_pk_mul_f32 v[16:17], v[0:1], v[16:17] op_sel_hi:[0,1]
	v_pk_mul_f32 v[14:15], v[0:1], v[14:15] op_sel_hi:[0,1]
	v_cvt_pk_bf16_f32 v2, v2, v3
	v_cvt_pk_bf16_f32 v3, v4, v5
	v_cvt_pk_bf16_f32 v4, v6, v7
	v_cvt_pk_bf16_f32 v5, v8, v9
	v_and_b32_e32 v0, 0xffffff80, v136
	s_waitcnt vmcnt(0)
	ds_write_b128 v131, v[2:5] offset:16192
	v_add_u32_e32 v2, s48, v0
	v_ashrrev_i32_e32 v3, 31, v2
	v_lshlrev_b64 v[2:3], 11, v[2:3]
	v_lshl_add_u64 v[2:3], s[42:43], 0, v[2:3]
	v_and_b32_e32 v0, 64, v136
	v_lshl_add_u64 v[2:3], s[46:47], 1, v[2:3]
	v_lshlrev_b32_e32 v0, 1, v0
	v_lshl_add_u64 v[6:7], v[2:3], 0, v[0:1]
	v_lshlrev_b32_e32 v0, 4, v136
	v_and_b32_e32 v0, 0x70, v0
	v_cvt_pk_bf16_f32 v122, v122, v123
	v_cvt_pk_bf16_f32 v123, v124, v125
	v_cvt_pk_bf16_f32 v124, v126, v127
	v_cvt_pk_bf16_f32 v125, v128, v129
	v_cvt_pk_bf16_f32 v114, v114, v115
	v_cvt_pk_bf16_f32 v115, v116, v117
	v_cvt_pk_bf16_f32 v116, v118, v119
	v_cvt_pk_bf16_f32 v117, v120, v121
	v_cvt_pk_bf16_f32 v106, v106, v107
	v_cvt_pk_bf16_f32 v107, v108, v109
	v_cvt_pk_bf16_f32 v108, v110, v111
	v_cvt_pk_bf16_f32 v109, v112, v113
	v_cvt_pk_bf16_f32 v98, v98, v99
	v_cvt_pk_bf16_f32 v99, v100, v101
	v_cvt_pk_bf16_f32 v100, v102, v103
	v_cvt_pk_bf16_f32 v101, v104, v105
	v_cvt_pk_bf16_f32 v90, v90, v91
	v_cvt_pk_bf16_f32 v91, v92, v93
	v_cvt_pk_bf16_f32 v92, v94, v95
	v_cvt_pk_bf16_f32 v93, v96, v97
	v_cvt_pk_bf16_f32 v82, v82, v83
	v_cvt_pk_bf16_f32 v83, v84, v85
	v_cvt_pk_bf16_f32 v84, v86, v87
	v_cvt_pk_bf16_f32 v85, v88, v89
	v_cvt_pk_bf16_f32 v74, v74, v75
	v_cvt_pk_bf16_f32 v75, v76, v77
	v_cvt_pk_bf16_f32 v76, v78, v79
	v_cvt_pk_bf16_f32 v77, v80, v81
	v_cvt_pk_bf16_f32 v66, v66, v67
	v_cvt_pk_bf16_f32 v67, v68, v69
	v_cvt_pk_bf16_f32 v68, v70, v71
	v_cvt_pk_bf16_f32 v69, v72, v73
	v_cvt_pk_bf16_f32 v58, v58, v59
	v_cvt_pk_bf16_f32 v59, v60, v61
	v_cvt_pk_bf16_f32 v60, v62, v63
	v_cvt_pk_bf16_f32 v61, v64, v65
	v_cvt_pk_bf16_f32 v50, v50, v51
	v_cvt_pk_bf16_f32 v51, v52, v53
	v_cvt_pk_bf16_f32 v52, v54, v55
	v_cvt_pk_bf16_f32 v53, v56, v57
	v_cvt_pk_bf16_f32 v42, v42, v43
	v_cvt_pk_bf16_f32 v43, v44, v45
	v_cvt_pk_bf16_f32 v44, v46, v47
	v_cvt_pk_bf16_f32 v45, v48, v49
	v_cvt_pk_bf16_f32 v34, v34, v35
	v_cvt_pk_bf16_f32 v35, v36, v37
	v_cvt_pk_bf16_f32 v36, v38, v39
	v_cvt_pk_bf16_f32 v37, v40, v41
	v_cvt_pk_bf16_f32 v26, v26, v27
	v_cvt_pk_bf16_f32 v27, v28, v29
	v_cvt_pk_bf16_f32 v28, v30, v31
	v_cvt_pk_bf16_f32 v29, v32, v33
	v_cvt_pk_bf16_f32 v18, v18, v19
	v_cvt_pk_bf16_f32 v19, v20, v21
	v_cvt_pk_bf16_f32 v20, v22, v23
	v_cvt_pk_bf16_f32 v21, v24, v25
	v_cvt_pk_bf16_f32 v10, v10, v11
	v_cvt_pk_bf16_f32 v11, v12, v13
	v_cvt_pk_bf16_f32 v12, v14, v15
	v_cvt_pk_bf16_f32 v13, v16, v17
	v_bfe_u32 v8, v136, 3, 3
	v_or_b32_e32 v2, v130, v0
	ds_write_b128 v131, v[122:125]
	ds_write_b128 v131, v[114:117] offset:64
	ds_write_b128 v131, v[106:109] offset:2304
	ds_write_b128 v131, v[98:101] offset:2368
	ds_write_b128 v131, v[90:93] offset:4608
	ds_write_b128 v131, v[82:85] offset:4672
	ds_write_b128 v131, v[74:77] offset:6912
	ds_write_b128 v131, v[66:69] offset:6976
	ds_write_b128 v131, v[58:61] offset:9216
	ds_write_b128 v131, v[50:53] offset:9280
	ds_write_b128 v131, v[42:45] offset:11520
	ds_write_b128 v131, v[34:37] offset:11584
	ds_write_b128 v131, v[26:29] offset:13824
	ds_write_b128 v131, v[18:21] offset:13888
	ds_write_b128 v131, v[10:13] offset:16128
	s_waitcnt lgkmcnt(0)
	v_mad_u32_u24 v10, v8, s4, v2
	ds_read_b128 v[66:69], v10
	ds_read_b128 v[70:73], v10 offset:1152
	ds_read_b128 v[74:77], v10 offset:2304
	ds_read_b128 v[78:81], v10 offset:3456
	ds_read_b128 v[82:85], v10 offset:4608
	ds_read_b128 v[86:89], v10 offset:5760
	ds_read_b128 v[90:93], v10 offset:6912
	ds_read_b128 v[94:97], v10 offset:8064
	ds_read_b128 v[98:101], v10 offset:9216
	ds_read_b128 v[102:105], v10 offset:10368
	ds_read_b128 v[106:109], v10 offset:11520
	ds_read_b128 v[110:113], v10 offset:12672
	ds_read_b128 v[114:117], v10 offset:13824
	ds_read_b128 v[118:121], v10 offset:14976
	ds_read_b128 v[122:125], v10 offset:16128
	ds_read_b128 v[126:129], v10 offset:17280
	v_lshl_add_u64 v[6:7], v[6:7], 0, v[0:1]
	v_lshlrev_b32_e32 v0, 11, v8
	v_lshl_add_u64 v[8:9], v[6:7], 0, v[0:1]
	s_waitcnt lgkmcnt(15)
	global_store_dwordx4 v[8:9], v[66:69], off
	v_or_b32_e32 v8, 0x4000, v0
	v_mov_b32_e32 v9, v1
	v_lshl_add_u64 v[8:9], v[6:7], 0, v[8:9]
	s_waitcnt lgkmcnt(14)
	global_store_dwordx4 v[8:9], v[70:73], off
	v_or_b32_e32 v8, 0x8000, v0
	v_mov_b32_e32 v9, v1
	v_lshl_add_u64 v[8:9], v[6:7], 0, v[8:9]
	s_waitcnt lgkmcnt(13)
	global_store_dwordx4 v[8:9], v[74:77], off
	v_or_b32_e32 v8, 0xc000, v0
	v_mov_b32_e32 v9, v1
	v_lshl_add_u64 v[8:9], v[6:7], 0, v[8:9]
	s_waitcnt lgkmcnt(12)
	global_store_dwordx4 v[8:9], v[78:81], off
	v_or_b32_e32 v8, 0x10000, v0
	v_mov_b32_e32 v9, v1
	v_lshl_add_u64 v[8:9], v[6:7], 0, v[8:9]
	s_waitcnt lgkmcnt(11)
	global_store_dwordx4 v[8:9], v[82:85], off
	v_or_b32_e32 v8, 0x14000, v0
	v_mov_b32_e32 v9, v1
	v_lshl_add_u64 v[8:9], v[6:7], 0, v[8:9]
	s_waitcnt lgkmcnt(10)
	global_store_dwordx4 v[8:9], v[86:89], off
	v_or_b32_e32 v8, 0x18000, v0
	v_mov_b32_e32 v9, v1
	v_lshl_add_u64 v[8:9], v[6:7], 0, v[8:9]
	s_waitcnt lgkmcnt(9)
	global_store_dwordx4 v[8:9], v[90:93], off
	v_or_b32_e32 v8, 0x1c000, v0
	v_mov_b32_e32 v9, v1
	v_lshl_add_u64 v[8:9], v[6:7], 0, v[8:9]
	s_waitcnt lgkmcnt(8)
	global_store_dwordx4 v[8:9], v[94:97], off
	v_or_b32_e32 v8, 0x20000, v0
	v_mov_b32_e32 v9, v1
	v_lshl_add_u64 v[8:9], v[6:7], 0, v[8:9]
	s_waitcnt lgkmcnt(7)
	global_store_dwordx4 v[8:9], v[98:101], off
	v_or_b32_e32 v8, 0x24000, v0
	v_mov_b32_e32 v9, v1
	v_lshl_add_u64 v[8:9], v[6:7], 0, v[8:9]
	s_waitcnt lgkmcnt(6)
	global_store_dwordx4 v[8:9], v[102:105], off
	v_or_b32_e32 v8, 0x28000, v0
	v_mov_b32_e32 v9, v1
	v_lshl_add_u64 v[8:9], v[6:7], 0, v[8:9]
	s_waitcnt lgkmcnt(5)
	global_store_dwordx4 v[8:9], v[106:109], off
	v_or_b32_e32 v8, 0x2c000, v0
	v_mov_b32_e32 v9, v1
	v_lshl_add_u64 v[8:9], v[6:7], 0, v[8:9]
	s_waitcnt lgkmcnt(4)
	global_store_dwordx4 v[8:9], v[110:113], off
	v_or_b32_e32 v8, 0x30000, v0
	v_mov_b32_e32 v9, v1
	v_lshl_add_u64 v[8:9], v[6:7], 0, v[8:9]
	s_waitcnt lgkmcnt(3)
	global_store_dwordx4 v[8:9], v[114:117], off
	v_or_b32_e32 v8, 0x34000, v0
	v_mov_b32_e32 v9, v1
	v_lshl_add_u64 v[8:9], v[6:7], 0, v[8:9]
	s_waitcnt lgkmcnt(2)
	global_store_dwordx4 v[8:9], v[118:121], off
	v_or_b32_e32 v8, 0x38000, v0
	v_mov_b32_e32 v9, v1
	v_lshl_add_u64 v[8:9], v[6:7], 0, v[8:9]
	v_or_b32_e32 v0, 0x3c000, v0
	s_waitcnt lgkmcnt(1)
	global_store_dwordx4 v[8:9], v[122:125], off
	v_lshl_add_u64 v[6:7], v[6:7], 0, v[0:1]
	s_waitcnt lgkmcnt(0)
	global_store_dwordx4 v[6:7], v[126:129], off
	s_waitcnt lgkmcnt(0)
	s_barrier
	s_branch .LBB0_236
